# cache_shift copy loop unrolled 4x (8 loads in flight per lane instead of 1)
# speedup vs baseline: 1.0068x; 1.0068x over previous
; DI void cache_shift(ArgsP a, int gt, int NT) {
;     for (int i = gt; i < 4 * 128 * 124 * 32; i += NT) { const int c4 = i & 31, j = (i >> 5) % 124, lb = (i >> 5) / 124;
;         *(f32x4*)(a->out + OFF_KS + ((size_t)lb * 128 + j) * 128 + c4 * 4) = *(const f32x4*)(a->in[2] + ((size_t)lb * 128 + j + 4) * 128 + c4 * 4);
;         *(f32x4*)(a->out + OFF_VS + ((size_t)lb * 128 + j) * 128 + c4 * 4) = *(const f32x4*)(a->in[3] + ((size_t)lb * 128 + j + 4) * 128 + c4 * 4); }
.LBB0_180:
	s_waitcnt lgkmcnt(0)
	v_and_b32_e32 v6, 0x7c, v2
	v_lshlrev_b32_e32 v96, 2, v6
	v_ashrrev_i32_e32 v5, 5, v3
	v_mul_hi_i32 v4, v5, s16
	v_add_u32_e32 v4, v4, v5
	v_lshrrev_b32_e32 v6, 31, v4
	v_ashrrev_i32_e32 v4, 6, v4
	v_add_u32_e32 v4, v4, v6
	v_mul_lo_u32 v6, v4, s17
	v_sub_u32_e32 v6, v5, v6
	v_ashrrev_i32_e32 v5, 31, v4
	v_ashrrev_i32_e32 v7, 31, v6
	v_lshlrev_b64 v[4:5], 14, v[4:5]
	v_lshlrev_b64 v[6:7], 7, v[6:7]
	v_lshl_add_u64 v[4:5], v[4:5], 0, v[6:7]
	v_lshlrev_b64 v[4:5], 2, v[4:5]
	v_lshl_add_u64 v[16:17], v[4:5], 0, v[96:97]
	v_lshl_add_u64 v[4:5], s[8:9], 0, v[16:17]
	global_load_dwordx4 v[24:27], v[4:5], off offset:2048
	v_lshl_add_u64 v[6:7], s[10:11], 0, v[16:17]
	global_load_dwordx4 v[28:31], v[6:7], off offset:2048
	v_add_u32_e32 v12, s14, v3
	v_cmp_ge_i32_e32 vcc, s18, v12
	s_and_b64 exec, exec, vcc
	v_ashrrev_i32_e32 v5, 5, v12
	v_mul_hi_i32 v4, v5, s16
	v_add_u32_e32 v4, v4, v5
	v_lshrrev_b32_e32 v6, 31, v4
	v_ashrrev_i32_e32 v4, 6, v4
	v_add_u32_e32 v4, v4, v6
	v_mul_lo_u32 v6, v4, s17
	v_sub_u32_e32 v6, v5, v6
	v_ashrrev_i32_e32 v5, 31, v4
	v_ashrrev_i32_e32 v7, 31, v6
	v_lshlrev_b64 v[4:5], 14, v[4:5]
	v_lshlrev_b64 v[6:7], 7, v[6:7]
	v_lshl_add_u64 v[4:5], v[4:5], 0, v[6:7]
	v_lshlrev_b64 v[4:5], 2, v[4:5]
	v_lshl_add_u64 v[18:19], v[4:5], 0, v[96:97]
	v_lshl_add_u64 v[4:5], s[8:9], 0, v[18:19]
	global_load_dwordx4 v[32:35], v[4:5], off offset:2048
	v_lshl_add_u64 v[6:7], s[10:11], 0, v[18:19]
	global_load_dwordx4 v[36:39], v[6:7], off offset:2048
	v_add_u32_e32 v12, s14, v12
	v_cmp_ge_i32_e32 vcc, s18, v12
	s_and_b64 exec, exec, vcc
	v_ashrrev_i32_e32 v5, 5, v12
	v_mul_hi_i32 v4, v5, s16
	v_add_u32_e32 v4, v4, v5
	v_lshrrev_b32_e32 v6, 31, v4
	v_ashrrev_i32_e32 v4, 6, v4
	v_add_u32_e32 v4, v4, v6
	v_mul_lo_u32 v6, v4, s17
	v_sub_u32_e32 v6, v5, v6
	v_ashrrev_i32_e32 v5, 31, v4
	v_ashrrev_i32_e32 v7, 31, v6
	v_lshlrev_b64 v[4:5], 14, v[4:5]
	v_lshlrev_b64 v[6:7], 7, v[6:7]
	v_lshl_add_u64 v[4:5], v[4:5], 0, v[6:7]
	v_lshlrev_b64 v[4:5], 2, v[4:5]
	v_lshl_add_u64 v[20:21], v[4:5], 0, v[96:97]
	v_lshl_add_u64 v[4:5], s[8:9], 0, v[20:21]
	global_load_dwordx4 v[40:43], v[4:5], off offset:2048
	v_lshl_add_u64 v[6:7], s[10:11], 0, v[20:21]
	global_load_dwordx4 v[44:47], v[6:7], off offset:2048
	v_add_u32_e32 v12, s14, v12
	v_cmp_ge_i32_e32 vcc, s18, v12
	s_and_b64 exec, exec, vcc
	v_ashrrev_i32_e32 v5, 5, v12
	v_mul_hi_i32 v4, v5, s16
	v_add_u32_e32 v4, v4, v5
	v_lshrrev_b32_e32 v6, 31, v4
	v_ashrrev_i32_e32 v4, 6, v4
	v_add_u32_e32 v4, v4, v6
	v_mul_lo_u32 v6, v4, s17
	v_sub_u32_e32 v6, v5, v6
	v_ashrrev_i32_e32 v5, 31, v4
	v_ashrrev_i32_e32 v7, 31, v6
	v_lshlrev_b64 v[4:5], 14, v[4:5]
	v_lshlrev_b64 v[6:7], 7, v[6:7]
	v_lshl_add_u64 v[4:5], v[4:5], 0, v[6:7]
	v_lshlrev_b64 v[4:5], 2, v[4:5]
	v_lshl_add_u64 v[22:23], v[4:5], 0, v[96:97]
	v_lshl_add_u64 v[4:5], s[8:9], 0, v[22:23]
	global_load_dwordx4 v[48:51], v[4:5], off offset:2048
	v_lshl_add_u64 v[6:7], s[10:11], 0, v[22:23]
	global_load_dwordx4 v[52:55], v[6:7], off offset:2048
	s_waitcnt vmcnt(0)
	s_mov_b64 exec, s[2:3]
	v_cmp_ge_i32_e32 vcc, s18, v0
	s_and_b64 exec, exec, vcc
	s_andn2_b64 exec, exec, s[12:13]
	v_lshl_add_u64 v[4:5], s[4:5], 0, v[16:17]
	global_store_dwordx4 v[4:5], v[24:27], off
	v_lshl_add_u64 v[6:7], s[6:7], 0, v[16:17]
	global_store_dwordx4 v[6:7], v[28:31], off
	v_add_u32_e32 v12, s14, v3
	v_cmp_ge_i32_e32 vcc, s18, v12
	s_and_b64 exec, exec, vcc
	v_lshl_add_u64 v[4:5], s[4:5], 0, v[18:19]
	global_store_dwordx4 v[4:5], v[32:35], off
	v_lshl_add_u64 v[6:7], s[6:7], 0, v[18:19]
	global_store_dwordx4 v[6:7], v[36:39], off
	v_add_u32_e32 v12, s14, v12
	v_cmp_ge_i32_e32 vcc, s18, v12
	s_and_b64 exec, exec, vcc
	v_lshl_add_u64 v[4:5], s[4:5], 0, v[20:21]
	global_store_dwordx4 v[4:5], v[40:43], off
	v_lshl_add_u64 v[6:7], s[6:7], 0, v[20:21]
	global_store_dwordx4 v[6:7], v[44:47], off
	v_add_u32_e32 v12, s14, v12
	v_cmp_ge_i32_e32 vcc, s18, v12
	s_and_b64 exec, exec, vcc
	v_lshl_add_u64 v[4:5], s[4:5], 0, v[22:23]
	global_store_dwordx4 v[4:5], v[48:51], off
	v_lshl_add_u64 v[6:7], s[6:7], 0, v[22:23]
	global_store_dwordx4 v[6:7], v[52:55], off
	s_mov_b64 exec, s[2:3]
	v_cmp_ge_i32_e32 vcc, s18, v0
	s_and_b64 exec, exec, vcc
	s_andn2_b64 exec, exec, s[12:13]
	v_lshl_add_u32 v3, s14, 2, v3
	v_cmp_lt_i32_e32 vcc, s18, v3
	s_or_b64 s[12:13], vcc, s[12:13]
	s_andn2_b64 exec, exec, s[12:13]
	s_cbranch_execnz .LBB0_180
